# one static s_setprio 1 for waves 4-7 during the P1 and P8 GEMM unit loops (no other setprio)
# baseline (speedup 1.0000x reference)
.LBB0_322:
	s_lshl_b32 s15, s14, 5
	s_mov_b64 s[10:11], 0x80
	s_and_b32 s50, s15, 0x60
	s_add_i32 m0, s40, 0x18000
	v_lshl_add_u64 v[8:9], v[8:9], 0, s[10:11]
	s_lshl_b32 s45, s7, 6
	s_lshl_b32 s5, s7, 13
	s_lshl_b32 s20, s50, 7
	s_waitcnt vmcnt(2)
	s_barrier
	global_load_lds_dwordx4 v[8:9], off
	v_lshl_add_u64 v[6:7], v[6:7], 0, s[10:11]
	s_add_i32 m0, s40, 0x1a000
	s_add_i32 s51, s40, 0x8000
	s_add_i32 s52, s40, 0xa000
	global_load_lds_dwordx4 v[6:7], off
	v_lshl_add_u64 v[2:3], v[2:3], 0, s[10:11]
	s_mov_b32 m0, s51
	s_add_u32 s18, s30, 0x40080
	global_load_lds_dwordx4 v[2:3], off
	v_lshl_add_u64 v[2:3], v[4:5], 0, s[10:11]
	s_mov_b32 m0, s52
	s_addc_u32 s19, s31, 0
	global_load_lds_dwordx4 v[2:3], off
	s_add_i32 m0, s40, 0x1c000
	v_lshl_add_u64 v[2:3], s[18:19], 0, v[202:203]
	global_load_lds_dwordx4 v[2:3], off
	v_lshl_add_u64 v[2:3], s[18:19], 0, v[198:199]
	s_add_i32 m0, s40, 0x1e000
	v_lshlrev_b32_e32 v4, 2, v216
	global_load_lds_dwordx4 v[2:3], off
	v_and_b32_e32 v2, 48, v0
	v_lshl_or_b32 v3, v216, 6, v2
	v_or_b32_e32 v2, v217, v2
	v_and_b32_e32 v4, 32, v4
	v_bitop3_b32 v225, s20, v2, v218 bitop3:0xf6
	v_lshlrev_b32_e32 v2, 8, v0
	v_bitop3_b32 v3, v3, s5, v4 bitop3:0xde
	v_and_b32_e32 v2, 0x18000, v2
	v_lshlrev_b32_e32 v4, 11, v12
	v_and_or_b32 v227, v0, 31, s15
	s_lshl_b32 s14, s14, 7
	s_add_i32 s15, 0, 0x21000
	v_or3_b32 v2, v10, v2, v4
	s_add_i32 s14, s15, s14
	v_add_u32_e32 v206, v2, v11
	v_lshlrev_b32_e32 v2, 4, v13
	s_waitcnt vmcnt(6)
	s_cmpk_lt_u32 s6, 0x100
	v_and_b32_e32 v2, 0x38000, v2
	s_cselect_b64 s[18:19], -1, 0
	s_lshl_b32 s6, s7, 8
	v_or3_b32 v2, v10, v2, v4
	s_sext_i32_i16 s2, s4
	v_lshrrev_b32_e32 v224, 4, v252
	v_cmp_gt_u32_e64 s[4:5], 32, v252
	v_lshl_add_u32 v228, v252, 2, s14
	s_add_i32 s14, s15, s6
	s_ashr_i32 s15, s3, 31
	v_mov_b32_e32 v207, v203
	v_add_u32_e32 v208, v2, v11
	v_mov_b32_e32 v209, v203
	v_mov_b64_e32 v[210:211], 0x580
	v_mov_b64_e32 v[212:213], 0x57f
	s_add_i32 s53, 0, 0x10000
	s_add_i32 s54, 0, 0x14000
	v_add_u32_e32 v229, 0, v3
	v_mov_b32_e32 v230, 0x358637bd
	s_movk_i32 s55, 0x1600
	s_barrier
	s_and_b64 vcc, exec, s[18:19]
	s_cbranch_vccnz .Lpr1_skip
	s_setprio 1
.Lpr1_skip:
	s_branch .LBB0_325
.LBB0_323:
	s_mov_b64 s[6:7], 0

.LBB0_340:
	s_setprio 0
	s_waitcnt vmcnt(0)
	s_barrier

.LBB0_1758:
	s_lshl_b32 s15, s14, 5
	s_mov_b64 s[16:17], 0x80
	s_and_b32 s50, s15, 0x60
	s_add_i32 m0, s40, 0x18000
	v_lshl_add_u64 v[8:9], v[8:9], 0, s[16:17]
	s_lshl_b32 s45, s7, 6
	s_lshl_b32 s5, s7, 13
	s_lshl_b32 s20, s50, 7
	s_waitcnt vmcnt(2)
	s_barrier
	global_load_lds_dwordx4 v[8:9], off
	v_lshl_add_u64 v[6:7], v[6:7], 0, s[16:17]
	s_add_i32 m0, s40, 0x1a000
	s_add_i32 s51, s40, 0x8000
	s_add_i32 s52, s40, 0xa000
	global_load_lds_dwordx4 v[6:7], off
	v_lshl_add_u64 v[2:3], v[2:3], 0, s[16:17]
	s_mov_b32 m0, s51
	s_add_u32 s18, s30, 0x40080
	global_load_lds_dwordx4 v[2:3], off
	v_lshl_add_u64 v[2:3], v[4:5], 0, s[16:17]
	s_mov_b32 m0, s52
	s_addc_u32 s19, s31, 0
	global_load_lds_dwordx4 v[2:3], off
	s_add_i32 m0, s40, 0x1c000
	v_lshl_add_u64 v[2:3], s[18:19], 0, v[202:203]
	global_load_lds_dwordx4 v[2:3], off
	v_lshl_add_u64 v[2:3], s[18:19], 0, v[198:199]
	s_add_i32 m0, s40, 0x1e000
	s_sext_i32_i16 s2, s4
	global_load_lds_dwordx4 v[2:3], off
	v_and_b32_e32 v1, 15, v0
	v_and_b32_e32 v2, 48, v0
	v_lshlrev_b32_e32 v4, 2, v0
	v_lshlrev_b32_e32 v5, 6, v0
	s_movk_i32 s4, 0x3c0
	v_lshl_or_b32 v3, v1, 6, v2
	v_and_b32_e32 v4, 32, v4
	v_and_or_b32 v2, v5, s4, v2
	v_bitop3_b32 v217, s20, v2, v4 bitop3:0xf6
	v_lshlrev_b32_e32 v2, 8, v0
	v_bitop3_b32 v3, v3, s5, v4 bitop3:0xde
	v_and_b32_e32 v2, 0x18000, v2
	v_lshlrev_b32_e32 v4, 11, v13
	v_and_or_b32 v218, v0, 31, s15
	s_lshl_b32 s14, s14, 7
	s_add_i32 s15, 0, 0x21000
	v_or3_b32 v2, v11, v2, v4
	s_add_i32 s14, s15, s14
	v_add_u32_e32 v206, v2, v12
	v_lshlrev_b32_e32 v2, 4, v10
	s_waitcnt vmcnt(6)
	s_cmpk_lt_u32 s6, 0x100
	v_and_b32_e32 v2, 0x38000, v2
	s_cselect_b64 s[18:19], -1, 0
	s_lshl_b32 s6, s7, 8
	v_or3_b32 v2, v11, v2, v4
	v_lshrrev_b32_e32 v216, 4, v252
	v_cmp_gt_u32_e64 s[4:5], 32, v252
	v_lshl_add_u32 v219, v252, 2, s14
	s_add_i32 s14, s15, s6
	s_ashr_i32 s15, s3, 31
	v_mov_b32_e32 v207, v203
	v_add_u32_e32 v208, v2, v12
	v_mov_b32_e32 v209, v203
	v_mov_b64_e32 v[210:211], 0x580
	v_mov_b64_e32 v[212:213], 0x57f
	s_add_i32 s53, 0, 0x10000
	s_add_i32 s54, 0, 0x14000
	v_add_u32_e32 v220, 0, v3
	v_mov_b32_e32 v221, 0x358637bd
	s_movk_i32 s55, 0x1600
	s_barrier
	s_and_b64 vcc, exec, s[18:19]
	s_cbranch_vccnz .Lpr8_skip
	s_setprio 1
.Lpr8_skip:
	s_branch .LBB0_1761
.LBB0_1759:
	s_mov_b64 s[6:7], 0
